# attention steady-state loops: exec-mask loop-exit test (v_cmp + s_or + s_andn2 exec + execz branch) replaced by a scalar compare and scc branch
# baseline (speedup 1.0000x reference)
.LBB0_1104:
	s_or_b64 exec, exec, s[2:3]
	v_and_or_b32 v18, v38, 32, v32
	v_sub_u32_e64 v19, v18, 8 clamp
	v_min_u32_e32 v19, 48, v19
	v_lshlrev_b32_e32 v207, 2, v36
	v_sub_u32_e32 v21, v207, v19
	v_sub_u32_e32 v22, v207, v18
	v_or_b32_e32 v20, 32, v207
	v_lshl_add_u32 v22, v22, 2, 60
	v_cmp_gt_u32_e32 vcc, 16, v21
	v_or_b32_e32 v23, 33, v207
	v_or_b32_e32 v25, 34, v207
	v_cndmask_b32_e32 v21, v250, v22, vcc
	v_sub_u32_e32 v22, v20, v19
	v_sub_u32_e32 v20, v20, v18
	v_cmp_gt_u32_e32 vcc, 16, v22
	v_or_b32_e32 v22, 1, v207
	v_lshl_add_u32 v20, v20, 2, 60
	v_sub_u32_e32 v24, v22, v19
	v_sub_u32_e32 v22, v22, v18
	v_cndmask_b32_e32 v20, v250, v20, vcc
	v_lshl_add_u32 v22, v22, 10, v251
	v_cmp_gt_u32_e32 vcc, 16, v24
	v_sub_u32_e32 v24, v23, v19
	v_sub_u32_e32 v23, v23, v18
	v_cndmask_b32_e32 v22, v242, v22, vcc
	v_cmp_gt_u32_e32 vcc, 16, v24
	v_or_b32_e32 v24, 2, v207
	v_lshl_add_u32 v23, v23, 10, v251
	v_sub_u32_e32 v26, v24, v19
	v_sub_u32_e32 v24, v24, v18
	v_cndmask_b32_e32 v23, v242, v23, vcc
	v_lshl_add_u32 v24, v24, 18, v243
	v_cmp_gt_u32_e32 vcc, 16, v26
	v_sub_u32_e32 v26, v25, v19
	v_sub_u32_e32 v25, v25, v18
	v_cndmask_b32_e32 v24, v244, v24, vcc
	v_cmp_gt_u32_e32 vcc, 16, v26
	v_or_b32_e32 v26, 3, v207
	v_lshl_add_u32 v25, v25, 18, v243
	v_sub_u32_e32 v28, v26, v19
	v_sub_u32_e32 v26, v26, v18
	v_cndmask_b32_e32 v25, v244, v25, vcc
	v_lshl_add_u32 v26, v26, 26, v245
	v_cmp_gt_u32_e32 vcc, 16, v28
	v_or_b32_e32 v27, 35, v207
	v_or_b32_e32 v29, 43, v207
	v_cndmask_b32_e32 v26, v227, v26, vcc
	v_or_b32_e32 v24, v24, v26
	v_or3_b32 v208, v24, v22, v21
	v_sub_u32_e32 v22, v27, v19
	v_sub_u32_e32 v24, v27, v18
	v_lshl_add_u32 v24, v24, 26, v245
	v_cmp_gt_u32_e32 vcc, 16, v22
	v_or_b32_e32 v27, 42, v207
	v_or_b32_e32 v31, 51, v207
	v_cndmask_b32_e32 v22, v227, v24, vcc
	v_or_b32_e32 v22, v25, v22
	v_or3_b32 v209, v22, v23, v20
	v_or_b32_e32 v22, 8, v207
	v_or_b32_e32 v23, 40, v207
	v_sub_u32_e32 v24, v22, v19
	v_sub_u32_e32 v22, v22, v18
	v_lshl_add_u32 v22, v22, 2, 60
	v_cmp_gt_u32_e32 vcc, 16, v24
	v_sub_u32_e32 v24, v23, v19
	v_sub_u32_e32 v23, v23, v18
	v_cndmask_b32_e32 v22, v250, v22, vcc
	v_cmp_gt_u32_e32 vcc, 16, v24
	v_or_b32_e32 v24, 9, v207
	v_lshl_add_u32 v23, v23, 2, 60
	v_or_b32_e32 v25, 41, v207
	v_sub_u32_e32 v26, v24, v19
	v_sub_u32_e32 v24, v24, v18
	v_cndmask_b32_e32 v23, v250, v23, vcc
	v_lshl_add_u32 v24, v24, 10, v251
	v_cmp_gt_u32_e32 vcc, 16, v26
	v_sub_u32_e32 v26, v25, v19
	v_sub_u32_e32 v25, v25, v18
	v_cndmask_b32_e32 v24, v242, v24, vcc
	v_cmp_gt_u32_e32 vcc, 16, v26
	v_or_b32_e32 v26, 10, v207
	v_lshl_add_u32 v25, v25, 10, v251
	v_sub_u32_e32 v28, v26, v19
	v_sub_u32_e32 v26, v26, v18
	v_cndmask_b32_e32 v25, v242, v25, vcc
	v_lshl_add_u32 v26, v26, 18, v243
	v_cmp_gt_u32_e32 vcc, 16, v28
	v_sub_u32_e32 v28, v27, v19
	v_sub_u32_e32 v27, v27, v18
	v_cndmask_b32_e32 v26, v244, v26, vcc
	v_cmp_gt_u32_e32 vcc, 16, v28
	v_or_b32_e32 v28, 11, v207
	v_lshl_add_u32 v27, v27, 18, v243
	v_sub_u32_e32 v30, v28, v19
	v_sub_u32_e32 v28, v28, v18
	v_cndmask_b32_e32 v27, v244, v27, vcc
	v_lshl_add_u32 v28, v28, 26, v245
	v_cmp_gt_u32_e32 vcc, 16, v30
	v_or_b32_e32 v34, 59, v207
	v_add3_u32 v216, 0, v37, v17
	v_cndmask_b32_e32 v28, v227, v28, vcc
	v_or_b32_e32 v26, v26, v28
	v_or3_b32 v210, v26, v24, v22
	v_sub_u32_e32 v24, v29, v19
	v_sub_u32_e32 v26, v29, v18
	v_lshl_add_u32 v26, v26, 26, v245
	v_cmp_gt_u32_e32 vcc, 16, v24
	v_or_b32_e32 v29, 50, v207
	v_lshrrev_b32_e32 v17, 2, v33
	v_cndmask_b32_e32 v24, v227, v26, vcc
	v_or_b32_e32 v24, v27, v24
	v_or3_b32 v211, v24, v25, v23
	v_or_b32_e32 v24, 16, v207
	v_or_b32_e32 v25, 48, v207
	v_sub_u32_e32 v26, v24, v19
	v_sub_u32_e32 v24, v24, v18
	v_lshl_add_u32 v24, v24, 2, 60
	v_cmp_gt_u32_e32 vcc, 16, v26
	v_sub_u32_e32 v26, v25, v19
	v_sub_u32_e32 v25, v25, v18
	v_cndmask_b32_e32 v24, v250, v24, vcc
	v_cmp_gt_u32_e32 vcc, 16, v26
	v_or_b32_e32 v26, 17, v207
	v_lshl_add_u32 v25, v25, 2, 60
	v_or_b32_e32 v27, 49, v207
	v_sub_u32_e32 v28, v26, v19
	v_sub_u32_e32 v26, v26, v18
	v_cndmask_b32_e32 v25, v250, v25, vcc
	v_lshl_add_u32 v26, v26, 10, v251
	v_cmp_gt_u32_e32 vcc, 16, v28
	v_sub_u32_e32 v28, v27, v19
	v_sub_u32_e32 v27, v27, v18
	v_cndmask_b32_e32 v26, v242, v26, vcc
	v_cmp_gt_u32_e32 vcc, 16, v28
	v_or_b32_e32 v28, 18, v207
	v_lshl_add_u32 v27, v27, 10, v251
	v_sub_u32_e32 v30, v28, v19
	v_sub_u32_e32 v28, v28, v18
	v_cndmask_b32_e32 v27, v242, v27, vcc
	v_lshl_add_u32 v28, v28, 18, v243
	v_cmp_gt_u32_e32 vcc, 16, v30
	v_sub_u32_e32 v30, v29, v19
	v_sub_u32_e32 v29, v29, v18
	v_cndmask_b32_e32 v28, v244, v28, vcc
	v_cmp_gt_u32_e32 vcc, 16, v30
	v_or_b32_e32 v30, 19, v207
	v_lshl_add_u32 v29, v29, 18, v243
	v_sub_u32_e32 v32, v30, v19
	v_sub_u32_e32 v30, v30, v18
	v_cndmask_b32_e32 v29, v244, v29, vcc
	v_lshl_add_u32 v30, v30, 26, v245
	v_cmp_gt_u32_e32 vcc, 16, v32
	v_and_or_b32 v17, v17, 3, v207
	v_mad_u32_u24 v17, v17, s20, 0
	v_cndmask_b32_e32 v30, v227, v30, vcc
	v_or_b32_e32 v28, v28, v30
	v_or3_b32 v212, v28, v26, v24
	v_sub_u32_e32 v26, v31, v19
	v_sub_u32_e32 v28, v31, v18
	v_lshl_add_u32 v28, v28, 26, v245
	v_cmp_gt_u32_e32 vcc, 16, v26
	v_or_b32_e32 v31, 58, v207
	v_lshlrev_b32_e32 v175, 7, v35
	v_cndmask_b32_e32 v26, v227, v28, vcc
	v_or_b32_e32 v26, v29, v26
	v_or3_b32 v213, v26, v27, v25
	v_or_b32_e32 v26, 24, v207
	v_or_b32_e32 v27, 56, v207
	v_sub_u32_e32 v28, v26, v19
	v_sub_u32_e32 v26, v26, v18
	v_lshl_add_u32 v26, v26, 2, 60
	v_cmp_gt_u32_e32 vcc, 16, v28
	v_sub_u32_e32 v28, v27, v19
	v_sub_u32_e32 v27, v27, v18
	v_cndmask_b32_e32 v26, v250, v26, vcc
	v_cmp_gt_u32_e32 vcc, 16, v28
	v_or_b32_e32 v28, 25, v207
	v_lshl_add_u32 v27, v27, 2, 60
	v_or_b32_e32 v29, 57, v207
	v_sub_u32_e32 v30, v28, v19
	v_sub_u32_e32 v28, v28, v18
	v_cndmask_b32_e32 v27, v250, v27, vcc
	v_lshl_add_u32 v28, v28, 10, v251
	v_cmp_gt_u32_e32 vcc, 16, v30
	v_sub_u32_e32 v30, v29, v19
	v_sub_u32_e32 v29, v29, v18
	v_cndmask_b32_e32 v28, v242, v28, vcc
	v_cmp_gt_u32_e32 vcc, 16, v30
	v_or_b32_e32 v30, 26, v207
	v_lshl_add_u32 v29, v29, 10, v251
	v_sub_u32_e32 v32, v30, v19
	v_sub_u32_e32 v30, v30, v18
	v_cndmask_b32_e32 v29, v242, v29, vcc
	v_lshl_add_u32 v30, v30, 18, v243
	v_cmp_gt_u32_e32 vcc, 16, v32
	v_sub_u32_e32 v32, v31, v19
	v_sub_u32_e32 v31, v31, v18
	v_cndmask_b32_e32 v30, v244, v30, vcc
	v_cmp_gt_u32_e32 vcc, 16, v32
	v_or_b32_e32 v32, 27, v207
	v_lshl_add_u32 v31, v31, 18, v243
	v_sub_u32_e32 v36, v32, v19
	v_sub_u32_e32 v32, v32, v18
	v_cndmask_b32_e32 v31, v244, v31, vcc
	v_lshl_add_u32 v32, v32, 26, v245
	v_cmp_gt_u32_e32 vcc, 16, v36
	v_sub_u32_e32 v19, v34, v19
	v_sub_u32_e32 v18, v34, v18
	v_cndmask_b32_e32 v32, v227, v32, vcc
	v_lshl_add_u32 v18, v18, 26, v245
	v_cmp_gt_u32_e32 vcc, 16, v19
	v_lshlrev_b32_e32 v19, 3, v33
	v_or_b32_e32 v30, v30, v32
	v_cndmask_b32_e32 v18, v227, v18, vcc
	v_or_b32_e32 v18, v31, v18
	v_or3_b32 v215, v18, v29, v27
	v_lshlrev_b32_e32 v18, 1, v33
	v_and_b32_e32 v18, 32, v18
	v_and_b32_e32 v19, 24, v19
	v_mov_b64_e32 v[46:47], v[14:15]
	v_mov_b64_e32 v[62:63], v[14:15]
	v_mov_b64_e32 v[78:79], v[14:15]
	v_or3_b32 v214, v30, v28, v26
	v_add3_u32 v217, v17, v18, v19
	v_cmp_lt_i32_e32 vcc, 3, v142
	v_mov_b32_e32 v180, 0
	v_mov_b32_e32 v143, 0
	v_and_b32_e32 v218, 0xfc, v21
	v_and_b32_e32 v219, 0xfc, v20
	v_and_b32_e32 v220, 0xfc, v22
	v_and_b32_e32 v221, 0xfc, v23
	v_and_b32_e32 v222, 0xfc, v24
	v_and_b32_e32 v223, 0xfc, v25
	v_and_b32_e32 v224, 0xfc, v26
	v_and_b32_e32 v225, 0xfc, v27
	v_mov_b64_e32 v[44:45], v[12:13]
	v_mov_b64_e32 v[42:43], v[10:11]
	v_mov_b64_e32 v[40:41], v[8:9]
	v_mov_b64_e32 v[38:39], v[6:7]
	v_mov_b64_e32 v[36:37], v[4:5]
	v_mov_b64_e32 v[34:35], v[2:3]
	v_mov_b64_e32 v[32:33], v[0:1]
	v_mov_b64_e32 v[60:61], v[12:13]
	v_mov_b64_e32 v[58:59], v[10:11]
	v_mov_b64_e32 v[56:57], v[8:9]
	v_mov_b64_e32 v[54:55], v[6:7]
	v_mov_b64_e32 v[52:53], v[4:5]
	v_mov_b64_e32 v[50:51], v[2:3]
	v_mov_b64_e32 v[48:49], v[0:1]
	v_mov_b64_e32 v[76:77], v[12:13]
	v_mov_b64_e32 v[74:75], v[10:11]
	v_mov_b64_e32 v[72:73], v[8:9]
	v_mov_b64_e32 v[70:71], v[6:7]
	v_mov_b64_e32 v[68:69], v[4:5]
	v_mov_b64_e32 v[66:67], v[2:3]
	v_mov_b64_e32 v[64:65], v[0:1]
	s_barrier
	s_and_saveexec_b64 s[8:9], vcc
	s_cbranch_execz .LBB0_1120
	v_lshlrev_b32_e32 v0, 7, v164
	v_sub_u32_e32 v0, v0, v175
	v_mov_b32_e32 v14, v113
	v_mov_b32_e32 v15, v113
	v_add_u32_e32 v181, 0, v0
	v_ashrrev_i32_e32 v143, 31, v142
	v_mov_b32_e32 v0, v113
	v_mov_b32_e32 v1, v113
	v_mov_b32_e32 v2, v113
	v_mov_b32_e32 v3, v113
	v_mov_b32_e32 v4, v113
	v_mov_b32_e32 v5, v113
	v_mov_b32_e32 v6, v113
	v_mov_b32_e32 v7, v113
	v_mov_b32_e32 v8, v113
	v_mov_b32_e32 v9, v113
	v_mov_b32_e32 v10, v113
	v_mov_b32_e32 v11, v113
	v_mov_b32_e32 v12, v113
	v_mov_b32_e32 v13, v113
	v_mov_b64_e32 v[46:47], v[14:15]
	v_mov_b64_e32 v[62:63], v[14:15]
	v_mov_b64_e32 v[78:79], v[14:15]
	v_add_u32_e32 v180, -3, v142
	v_mov_b32_e32 v17, v16
	v_mov_b32_e32 v18, v16
	v_mov_b32_e32 v19, v16
	v_mov_b32_e32 v20, v16
	v_mov_b32_e32 v21, v16
	v_mov_b32_e32 v22, v16
	v_mov_b32_e32 v23, v16
	v_mov_b32_e32 v24, v16
	v_mov_b32_e32 v25, v16
	v_mov_b32_e32 v26, v16
	v_mov_b32_e32 v27, v16
	v_mov_b32_e32 v28, v16
	v_mov_b32_e32 v29, v16
	v_mov_b32_e32 v30, v16
	v_mov_b32_e32 v31, v16
	v_mov_b32_e32 v165, v113
	v_lshl_add_u64 v[176:177], v[142:143], 0, -3
	s_nop 0
	v_readfirstlane_b32 s98, v176
	v_mov_b32_e32 v143, 0
	s_mov_b64 s[18:19], 0
	s_mov_b64 s[36:37], 0
	v_mov_b64_e32 v[44:45], v[12:13]
	v_mov_b64_e32 v[42:43], v[10:11]
	v_mov_b64_e32 v[40:41], v[8:9]
	v_mov_b64_e32 v[38:39], v[6:7]
	v_mov_b64_e32 v[36:37], v[4:5]
	v_mov_b64_e32 v[34:35], v[2:3]
	v_mov_b64_e32 v[32:33], v[0:1]
	v_mov_b64_e32 v[60:61], v[12:13]
	v_mov_b64_e32 v[58:59], v[10:11]
	v_mov_b64_e32 v[56:57], v[8:9]
	v_mov_b64_e32 v[54:55], v[6:7]
	v_mov_b64_e32 v[52:53], v[4:5]
	v_mov_b64_e32 v[50:51], v[2:3]
	v_mov_b64_e32 v[48:49], v[0:1]
	v_mov_b64_e32 v[76:77], v[12:13]
	v_mov_b64_e32 v[74:75], v[10:11]
	v_mov_b64_e32 v[72:73], v[8:9]
	v_mov_b64_e32 v[70:71], v[6:7]
	v_mov_b64_e32 v[68:69], v[4:5]
	v_mov_b64_e32 v[66:67], v[2:3]
	v_mov_b64_e32 v[64:65], v[0:1]
	s_branch .LBB0_1107
.LBB0_1106:
	s_or_b64 exec, exec, s[6:7]
	s_nop 0
	v_mov_b64_e32 v[94:95], v[78:79]
	v_mov_b64_e32 v[110:111], v[62:63]
	v_add_u32_e32 v181, 0x80, v181
	s_mov_b64 s[36:37], s[66:67]
	v_mov_b64_e32 v[92:93], v[76:77]
	v_mov_b64_e32 v[90:91], v[74:75]
	v_mov_b64_e32 v[88:89], v[72:73]
	v_mov_b64_e32 v[86:87], v[70:71]
	v_mov_b64_e32 v[84:85], v[68:69]
	v_mov_b64_e32 v[82:83], v[66:67]
	v_mov_b64_e32 v[80:81], v[64:65]
	v_mov_b64_e32 v[108:109], v[60:61]
	v_mov_b64_e32 v[106:107], v[58:59]
	v_mov_b64_e32 v[104:105], v[56:57]
	v_mov_b64_e32 v[102:103], v[54:55]
	v_mov_b64_e32 v[100:101], v[52:53]
	v_mov_b64_e32 v[98:99], v[50:51]
	v_mov_b64_e32 v[96:97], v[48:49]
	s_waitcnt lgkmcnt(0)
	s_barrier
	s_cmp_eq_u32 s66, s98
	s_cbranch_scc1 .LBB0_1119

.LBB0_1186:
	s_or_b64 exec, exec, s[2:3]
	v_lshlrev_b64 v[2:3], 6, v[24:25]
	v_lshlrev_b32_e32 v4, 3, v32
	v_lshl_add_u64 v[2:3], v[2:3], 1, v[12:13]
	v_lshlrev_b32_e32 v4, 1, v4
	v_mov_b32_e32 v5, v113
	v_lshl_add_u64 v[2:3], v[2:3], 0, v[4:5]
	v_add_co_u32_e32 v2, vcc, 0x2000, v2
	v_and_b32_e32 v6, 31, v29
	s_nop 0
	v_addc_co_u32_e32 v3, vcc, 0, v3, vcc
	global_load_dwordx4 v[204:207], v[2:3], off
	v_mul_u32_u24_e32 v2, 0xd0, v6
	v_add3_u32 v180, 0, v2, v22
	s_waitcnt lgkmcnt(0)
	s_barrier
	ds_read_b128 v[2:5], v180
	ds_read_b128 v[12:15], v180 offset:32
	v_xor_b32_e32 v32, 0x80000000, v28
	v_mov_b32_e32 v33, v32
	v_mov_b32_e32 v34, v32
	v_mov_b32_e32 v35, v32
	v_mov_b32_e32 v36, v32
	v_mov_b32_e32 v37, v32
	v_mov_b32_e32 v38, v32
	v_mov_b32_e32 v39, v32
	v_mov_b32_e32 v40, v32
	v_mov_b32_e32 v41, v32
	v_mov_b32_e32 v42, v32
	v_mov_b32_e32 v43, v32
	v_mov_b32_e32 v44, v32
	v_mov_b32_e32 v45, v32
	v_mov_b32_e32 v46, v32
	v_mov_b32_e32 v47, v32
	v_lshl_add_u64 v[0:1], v[0:1], 0, v[10:11]
	v_lshl_add_u64 v[0:1], v[18:19], 1, v[0:1]
	s_waitcnt lgkmcnt(0)
	v_mfma_f32_32x32x16_bf16 v[64:79], v[2:5], v[100:103], v[32:47]
	ds_read_b128 v[2:5], v180 offset:6656
	ds_read_b128 v[24:27], v180 offset:6688
	v_lshl_add_u64 v[142:143], s[12:13], 0, v[0:1]
	v_mad_i64_i32 v[0:1], s[2:3], v23, s22, v[10:11]
	v_lshlrev_b32_e32 v177, 2, v30
	v_lshrrev_b32_e32 v6, 2, v29
	v_lshl_add_u64 v[0:1], v[16:17], 1, v[0:1]
	s_waitcnt lgkmcnt(0)
	v_mfma_f32_32x32x16_bf16 v[48:63], v[2:5], v[100:103], v[32:47]
	v_and_or_b32 v6, v6, 3, v177
	v_lshlrev_b32_e32 v7, 1, v29
	v_lshl_add_u64 v[162:163], s[12:13], 0, v[0:1]
	v_lshl_add_u64 v[0:1], v[8:9], 0, v[20:21]
	v_mad_u32_u24 v6, v6, s20, 0
	v_and_b32_e32 v7, 32, v7
	v_lshl_add_u64 v[0:1], v[0:1], 0, v[112:113]
	v_mfma_f32_32x32x16_bf16 v[64:79], v[12:15], v[104:107], v[64:79]
	ds_read_b128 v[2:5], v180 offset:64
	ds_read_b128 v[12:15], v180 offset:96
	v_mov_b32_e32 v114, 0
	v_and_b32_e32 v178, 63, v29
	s_mov_b32 s34, 0
	v_add_u32_e32 v173, -3, v166
	s_nop 0
	v_readfirstlane_b32 s98, v173
	v_lshl_add_u64 v[164:165], s[14:15], 0, v[0:1]
	s_mov_b64 s[2:3], 0
	v_mfma_f32_32x32x16_bf16 v[48:63], v[24:27], v[104:107], v[48:63]
	v_mov_b32_e32 v0, 0
	v_mov_b32_e32 v1, v114
	v_mov_b32_e32 v8, v114
	v_mov_b32_e32 v9, v114
	v_mov_b32_e32 v10, v114
	v_mov_b32_e32 v11, v114
	v_mov_b32_e32 v16, 0
	s_waitcnt lgkmcnt(0)
	v_mfma_f32_32x32x16_bf16 v[64:79], v[2:5], v[108:111], v[64:79]
	ds_read_b128 v[2:5], v180 offset:6720
	ds_read_b128 v[24:27], v180 offset:6752
	v_mov_b32_e32 v17, v114
	v_mov_b32_e32 v18, v114
	v_mov_b32_e32 v19, v114
	v_mov_b32_e32 v20, v114
	v_mov_b32_e32 v21, v114
	v_mov_b32_e32 v22, v114
	s_waitcnt lgkmcnt(0)
	v_mfma_f32_32x32x16_bf16 v[48:63], v[2:5], v[108:111], v[48:63]
	ds_read_b128 v[2:5], v180 offset:128
	ds_read_b128 v[80:83], v180 offset:160
	ds_read_b128 v[84:87], v180 offset:6784
	ds_read_b128 v[88:91], v180 offset:6816
	v_mov_b32_e32 v23, v114
	v_mov_b32_e32 v28, v114
	v_mov_b32_e32 v30, v114
	v_mov_b32_e32 v31, v114
	s_waitcnt lgkmcnt(0)
	s_barrier
	v_mfma_f32_32x32x16_bf16 v[64:79], v[12:15], v[116:119], v[64:79]
	v_lshlrev_b32_e32 v12, 3, v29
	v_and_b32_e32 v12, 24, v12
	v_add3_u32 v179, v6, v7, v12
	v_mov_b32_e32 v6, v114
	v_mov_b32_e32 v7, v114
	v_mov_b32_e32 v12, v114
	v_mov_b32_e32 v13, v114
	v_mfma_f32_32x32x16_bf16 v[48:63], v[24:27], v[116:119], v[48:63]
	v_mov_b32_e32 v14, v114
	v_mov_b32_e32 v15, v114
	v_mov_b32_e32 v24, v114
	v_mov_b32_e32 v25, v114
	v_mov_b32_e32 v26, v114
	v_mov_b32_e32 v27, v114
	v_mov_b32_e32 v29, v114
	v_mfma_f32_32x32x16_bf16 v[64:79], v[2:5], v[120:123], v[64:79]
	v_mov_b32_e32 v2, v114
	v_mov_b32_e32 v3, v114
	v_mov_b32_e32 v4, v114
	v_mov_b32_e32 v5, v114
	v_mfma_f32_32x32x16_bf16 v[48:63], v[84:87], v[120:123], v[48:63]
	v_mfma_f32_32x32x16_bf16 v[64:79], v[80:83], v[96:99], v[64:79]
	v_mfma_f32_32x32x16_bf16 v[48:63], v[88:91], v[96:99], v[48:63]
	s_branch .LBB0_1188
.LBB0_1187:
	s_or_b64 exec, exec, s[36:37]
	s_add_i32 s34, s34, 1
	s_bitcmp1_b32 s34, 0
	s_cselect_b32 s36, 0x3400, 0
	v_add_u32_e32 v112, s36, v180
	ds_read_b128 v[132:135], v112
	ds_read_b128 v[136:139], v112 offset:32
	v_exp_f32_e32 v174, v48
	v_exp_f32_e32 v175, v49
	v_exp_f32_e32 v182, v50
	s_waitcnt lgkmcnt(0)
	v_mfma_f32_32x32x16_bf16 v[80:95], v[132:135], v[100:103], v[32:47]
	v_exp_f32_e32 v183, v51
	v_exp_f32_e32 v184, v52
	v_exp_f32_e32 v185, v53
	v_exp_f32_e32 v186, v54
	v_exp_f32_e32 v187, v55
	v_exp_f32_e32 v188, v56
	v_exp_f32_e32 v189, v57
	v_mfma_f32_32x32x16_bf16 v[80:95], v[136:139], v[104:107], v[80:95]
	ds_read_b128 v[132:135], v112 offset:64
	ds_read_b128 v[136:139], v112 offset:96
	v_exp_f32_e32 v190, v58
	v_exp_f32_e32 v191, v59
	v_exp_f32_e32 v192, v60
	v_exp_f32_e32 v193, v61
	v_exp_f32_e32 v194, v62
	v_exp_f32_e32 v195, v63
	s_waitcnt lgkmcnt(0)
	v_mfma_f32_32x32x16_bf16 v[80:95], v[132:135], v[108:111], v[80:95]
	ds_read_b128 v[132:135], v112 offset:128
	ds_read_b128 v[48:51], v112 offset:160
	s_and_b64 s[18:19], s[18:19], exec
	s_cselect_b32 s18, 0x2400, 0
	v_exp_f32_e32 v198, v64
	v_exp_f32_e32 v199, v65
	v_exp_f32_e32 v200, v70
	v_mfma_f32_32x32x16_bf16 v[80:95], v[136:139], v[116:119], v[80:95]
	v_exp_f32_e32 v201, v71
	v_exp_f32_e32 v202, v72
	v_exp_f32_e32 v203, v73
	v_exp_f32_e32 v76, v76
	v_cvt_pk_bf16_f32 v71, v200, v201
	v_exp_f32_e32 v78, v78
	v_exp_f32_e32 v79, v79
	s_waitcnt lgkmcnt(0)
	v_mfma_f32_32x32x16_bf16 v[80:95], v[132:135], v[120:123], v[80:95]
	ds_read_b128 v[132:135], v112 offset:6656
	ds_read_b128 v[146:149], v112 offset:6688
	v_exp_f32_e32 v77, v77
	v_lshl_add_u64 v[142:143], v[142:143], 0, s[24:25]
	v_lshl_add_u64 v[162:163], v[162:163], 0, s[24:25]
	v_mfma_f32_32x32x16_bf16 v[80:95], v[48:51], v[96:99], v[80:95]
	s_waitcnt lgkmcnt(0)
	v_mfma_f32_32x32x16_bf16 v[48:63], v[132:135], v[100:103], v[32:47]
	ds_read_b128 v[150:153], v112 offset:6720
	ds_read_b128 v[154:157], v112 offset:6752
	ds_read_b128 v[158:161], v112 offset:6784
	ds_read_b128 v[136:139], v112 offset:6816
	v_add_u32_e32 v112, s18, v179
	v_lshl_add_u64 v[164:165], v[164:165], 0, s[0:1]
	v_mfma_f32_32x32x16_bf16 v[48:63], v[146:149], v[104:107], v[48:63]
	v_exp_f32_e32 v146, v66
	v_exp_f32_e32 v147, v67
	v_exp_f32_e32 v148, v68
	v_exp_f32_e32 v149, v69
	ds_read_b64_tr_b16 v[64:65], v112 offset:26624
	ds_read_b64_tr_b16 v[66:67], v112 offset:27776
	v_cvt_pk_bf16_f32 v68, v198, v199
	v_cvt_pk_bf16_f32 v69, v146, v147
	s_waitcnt lgkmcnt(0)
	v_mfma_f32_32x32x16_bf16 v[48:63], v[150:153], v[108:111], v[48:63]
	v_exp_f32_e32 v150, v74
	v_exp_f32_e32 v151, v75
	ds_read_b64_tr_b16 v[74:75], v112 offset:27840
	ds_read_b64_tr_b16 v[72:73], v112 offset:26688
	v_cvt_pk_bf16_f32 v70, v148, v149
	v_pk_add_f32 v[146:147], v[182:183], v[146:147]
	v_pk_add_f32 v[198:199], v[174:175], v[198:199]
	v_pk_add_f32 v[148:149], v[184:185], v[148:149]
	v_mfma_f32_32x32x16_bf16 v[0:15], v[64:67], v[68:71], v[0:15]
	ds_read_b64_tr_b16 v[64:65], v112 offset:28928
	ds_read_b64_tr_b16 v[66:67], v112 offset:30080
	v_add_f32_e64 v152, v194, v78
	v_add_f32_e64 v153, v195, v79
	s_waitcnt lgkmcnt(0)
	v_mfma_f32_32x32x16_bf16 v[16:31], v[72:75], v[68:71], v[16:31]
	ds_read_b64_tr_b16 v[74:75], v112 offset:30144
	ds_read_b64_tr_b16 v[72:73], v112 offset:28992
	v_cvt_pk_bf16_f32 v68, v202, v203
	v_cvt_pk_bf16_f32 v69, v150, v151
	v_cvt_pk_bf16_f32 v70, v76, v77
	v_cvt_pk_bf16_f32 v71, v78, v79
	v_mfma_f32_32x32x16_bf16 v[48:63], v[154:157], v[116:119], v[48:63]
	v_add_f32_e64 v154, v192, v76
	v_add_f32_e64 v155, v193, v77
	v_add_f32_e64 v156, v190, v150
	v_add_f32_e64 v157, v191, v151
	v_mfma_f32_32x32x16_bf16 v[0:15], v[64:67], v[68:71], v[0:15]
	s_waitcnt lgkmcnt(0)
	v_mfma_f32_32x32x16_bf16 v[16:31], v[72:75], v[68:71], v[16:31]
	v_cvt_pk_bf16_f32 v68, v174, v175
	v_cvt_pk_bf16_f32 v69, v182, v183
	v_cvt_pk_bf16_f32 v70, v184, v185
	v_cvt_pk_bf16_f32 v71, v186, v187
	v_mfma_f32_32x32x16_bf16 v[48:63], v[158:161], v[120:123], v[48:63]
	v_add_f32_e64 v160, v186, v200
	v_add_f32_e64 v161, v187, v201
	v_pk_mov_b32 v[200:201], v[198:199], v[146:147] op_sel:[1,0]
	v_mov_b32_e32 v199, v147
	v_pk_add_f32 v[64:65], v[200:201], v[198:199]
	v_pk_mov_b32 v[78:79], v[148:149], v[160:161] op_sel:[1,0]
	v_pk_add_f32 v[76:77], v[64:65], v[64:65] op_sel_hi:[0,1]
	ds_read_b64_tr_b16 v[64:65], v112 offset:31232
	ds_read_b64_tr_b16 v[66:67], v112 offset:32384
	ds_read_b64_tr_b16 v[74:75], v112 offset:32448
	ds_read_b64_tr_b16 v[72:73], v112 offset:31296
	s_waitcnt lgkmcnt(0)
	v_mfma_f32_32x32x16_bf16 v[0:15], v[64:67], v[68:71], v[0:15]
	ds_read_b64_tr_b16 v[64:65], v112 offset:33536
	ds_read_b64_tr_b16 v[66:67], v112 offset:34688
	v_mov_b32_e32 v149, v161
	v_add_f32_e64 v78, v78, v148
	v_add_f32_e64 v79, v79, v149
	v_pk_add_f32 v[158:159], v[188:189], v[202:203]
	v_pk_add_f32 v[78:79], v[78:79], v[78:79] op_sel_hi:[0,1]
	v_add_f32_e32 v147, v158, v159
	v_add_f32_e32 v149, v156, v157
	v_mfma_f32_32x32x16_bf16 v[16:31], v[72:75], v[68:71], v[16:31]
	ds_read_b64_tr_b16 v[74:75], v112 offset:34752
	ds_read_b64_tr_b16 v[72:73], v112 offset:33600
	v_cvt_pk_bf16_f32 v68, v188, v189
	v_cvt_pk_bf16_f32 v69, v190, v191
	v_cvt_pk_bf16_f32 v70, v192, v193
	v_cvt_pk_bf16_f32 v71, v194, v195
	v_mov_b32_e32 v146, v154
	v_mov_b32_e32 v148, v155
	s_waitcnt lgkmcnt(0)
	v_mfma_f32_32x32x16_bf16 v[0:15], v[64:67], v[68:71], v[0:15]
	v_mov_b32_e32 v76, v152
	v_mov_b32_e32 v78, v153
	v_add_f32_e64 v146, v146, v148
	v_add_f32_e64 v147, v147, v149
	v_add_f32_e64 v64, v76, v78
	v_add_f32_e64 v65, v77, v79
	v_pk_add_f32 v[64:65], v[146:147], v[64:65]
	s_barrier
	v_mfma_f32_32x32x16_bf16 v[16:31], v[72:75], v[68:71], v[16:31]
	v_add_f32_e32 v64, v64, v65
	v_add_f32_e32 v114, v114, v64
	v_mov_b64_e32 v[64:65], v[80:81]
	v_mov_b64_e32 v[66:67], v[82:83]
	v_mov_b64_e32 v[68:69], v[84:85]
	v_mov_b64_e32 v[70:71], v[86:87]
	v_mov_b64_e32 v[72:73], v[88:89]
	v_mfma_f32_32x32x16_bf16 v[48:63], v[136:139], v[96:99], v[48:63]
	v_mov_b64_e32 v[74:75], v[90:91]
	v_mov_b64_e32 v[76:77], v[92:93]
	v_mov_b64_e32 v[78:79], v[94:95]
	s_cmp_eq_u32 s34, s98
	s_cbranch_scc1 .LBB0_1192
